# retention key tiles: V^T loads widened to dwordx4 with v_permlane32_swap (8 -> 4 loads per tile)
# baseline (speedup 1.0000x reference)
; #define MFMA32(a, b, c) __builtin_amdgcn_mfma_f32_32x32x16_bf16((a), (b), (c), 0, 0, 0)
;     DEVINL bf16_t* Z() const { return (bf16_t*)(ws + OFF_Z); }
;     DEVINL bf16_t* BVT() const { return (bf16_t*)(ws + OFF_BVT); }
;     DEVINL bf16_t* BKT() const { return (bf16_t*)(ws + OFF_BKT); }
;     DEVINL bf16_t* Y() const { return (bf16_t*)(ws + OFF_Y); }
; #define TID (opq_v((int)threadIdx.x))
; DEVINL bf16_t f2bf(float f) { return (bf16_t)(cvt_pk_bf16(f, 0.f) & 0xffffu); }
; DEVINL float fexp2(float x) { return __builtin_amdgcn_exp2f(x); }
; DEVINL void ret_block(const Ctx& c, int b, int hd, unsigned char* lds) {
;     bf16_t* ST = (bf16_t*)lds;
;     float* ssq = (float*)(lds + 128 * LROW);
;     const int tid = TID, lane = tid & 63, w = tid >> 6, r = lane & 31, h = lane >> 5;
;     const int qs = w & 3, dh = w >> 2, dvt = w >> 1, dt = w & 1;
;     const float lg2 = flog2(1.f - fexp2(-5.f - (float)hd));
;     const float gam = fexp2(lg2), gam128 = fexp2(lg2 * 128.f);
;     f32x16 sacc;
; #pragma unroll
;     for (int i = 0; i < 16; ++i) sacc[i] = 0.f;
;     const bf16_t* vtb = c.BVT() + (size_t)(b * 512 + hd * 128) * L;
;     const bf16_t* ktb = c.BKT() + (size_t)(b * 256 + hd * 64) * L;
;     bf16_t* Y = c.Y() + (size_t)T * 512;
;     for (int ch = 0; ch < L / 128; ++ch) {
;         const int t0 = b * L + ch * 128, p0 = ch * 128;
;         __syncthreads();
; #pragma unroll
;         for (int i = 0; i < 16; ++i) {
;             const int dv = dvt * 32 + (i & 3) + 8 * (i >> 2) + 4 * h;
;             ST[dv * 72 + dt * 32 + r] = f2bf(sacc[i]);
;         }
;         __syncthreads();
;         const int ql = qs * 32 + r;
;         bf16x8 qf[4];
;         const bf16_t* qp = c.Z() + (size_t)(t0 + ql) * ZW + Z_BQ + hd * 64 + 8 * h;
; #pragma unroll
;         for (int s = 0; s < 4; ++s) qf[s] = *(const bf16x8*)(qp + 16 * s);
;     ...
;             for (int d = 0; d < 2; ++d) {
;                 const bf16_t* vp = vtb + (size_t)(dh * 64 + d * 32 + r) * L + p0 + kt * 32 + 4 * h;
; #pragma unroll
;                 for (int s = 0; s < 2; ++s) {
;                     const u32x2 lo = *(const u32x2*)(vp + 16 * s), hi = *(const u32x2*)(vp + 16 * s + 8);
;                     u32x4 vv = {lo[0], lo[1], hi[0], hi[1]};
;                     o[d] = MFMA32(__builtin_bit_cast(bf16x8, vv), pf[s], o[d]);
;                 }
.LBB0_266:
	s_and_b64 vcc, exec, s[0:1]
	s_cbranch_vccz .LBB0_275
	s_and_b32 s12, s95, 3
	s_waitcnt vmcnt(0)
	v_cvt_f32_ubyte0_e32 v0, s12
	v_sub_f32_e32 v0, 0xc0a00000, v0
	v_exp_f32_e32 v0, v0
	v_mov_b32_e32 v2, v160
	s_sub_i32 s0, s95, 64
	v_sub_f32_e32 v0, 1.0, v0
	v_log_f32_e32 v93, v0
	v_ashrrev_i32_e32 v0, 6, v2
	v_and_b32_e32 v6, 1, v0
	v_lshlrev_b32_e32 v0, 5, v0
	v_and_b32_e32 v3, 31, v2
	v_and_b32_e32 v10, 0x60, v0
	v_mul_f32_e32 v1, 0x43000000, v93
	v_or_b32_e32 v92, v10, v3
	v_exp_f32_e32 v88, v1
	v_lshlrev_b32_e32 v1, 6, v6
	v_lshlrev_b32_e32 v9, 1, v3
	v_cvt_f32_ubyte0_e32 v0, v92
	v_add3_u32 v9, 0, v1, v9
	v_mul_f32_e32 v0, v93, v0
	v_and_b32_e32 v1, 64, v162
	s_lshr_b32 s13, s0, 2
	v_ashrrev_i32_e32 v5, 8, v2
	s_lshl_b32 s14, s12, 7
	v_exp_f32_e32 v98, v0
	v_xor_b32_e32 v0, 32, v162
	v_add_u32_e32 v1, 64, v1
	s_lshl_b32 s4, s12, 8
	v_readlane_b32 s5, v247, 53
	v_bfe_u32 v4, v2, 5, 1
	v_ashrrev_i32_e32 v7, 2, v2
	v_lshlrev_b32_e32 v94, 6, v5
	v_cmp_lt_i32_e32 vcc, v0, v1
	s_add_u32 s4, s5, s4
	v_readlane_b32 s5, v247, 54
	v_and_b32_e32 v8, 0xffffffe0, v7
	v_lshlrev_b32_e32 v90, 2, v4
	v_cndmask_b32_e32 v0, v162, v0, vcc
	v_ashrrev_i32_e32 v95, 31, v94
	s_addc_u32 s5, s5, 0
	v_lshlrev_b32_e32 v64, 3, v4
	v_or_b32_e32 v11, v94, v3
	v_lshlrev_b32_e32 v96, 4, v4
	v_lshlrev_b32_e32 v122, 2, v0
	v_cmp_eq_u32_e64 s[0:1], 0, v4
	v_lshl_add_u64 v[0:1], v[94:95], 1, s[4:5]
	v_lshl_or_b32 v4, v6, 5, v3
	v_or_b32_e32 v6, v90, v8
	s_movk_i32 s4, 0x90
	v_mul_lo_u32 v6, v6, s4
	v_mul_lo_u32 v8, v11, s4
	s_add_u32 s4, s26, s14
	s_addc_u32 s5, s27, 0
	v_mov_b32_e32 v97, v65
	s_movk_i32 s15, 0x1100
	v_lshl_add_u64 v[104:105], s[4:5], 0, v[96:97]
	v_lshl_add_u64 v[106:107], v[0:1], 0, v[64:65]
	v_mad_i64_i32 v[0:1], s[4:5], v11, s15, 0
	s_mul_i32 s4, s13, 0x110000
	s_mul_i32 s5, s12, 0x44000
	s_add_i32 s66, s4, s5
	s_lshl_b64 s[4:5], s[66:67], 1
	v_readlane_b32 s8, v246, 26
	s_add_u32 s8, s8, s4
	v_readlane_b32 s9, v246, 29
	v_or_b32_e32 v0, v0, v64
	s_addc_u32 s9, s9, s5
	v_lshl_add_u64 v[108:109], s[8:9], 0, v[0:1]
	v_or_b32_e32 v0, 32, v11
	v_mad_i64_i32 v[0:1], s[10:11], v0, s15, 0
	v_or_b32_e32 v0, v0, v64
	v_lshl_add_u64 v[110:111], s[8:9], 0, v[0:1]
	s_movk_i32 s8, 0xffe0
	v_bfi_b32 v2, s8, v7, v2
	v_readlane_b32 s8, v246, 27
	v_readlane_b32 s9, v246, 28
	s_add_u32 s4, s8, s4
	s_addc_u32 s5, s9, s5
	v_mov_b64_e32 v[0:1], s[4:5]
	v_mad_i64_i32 v[112:113], s[4:5], v2, s15, v[0:1]
	s_mul_i32 s4, s13, 0x88000
	s_mul_i32 s12, s12, 0x22000
	v_exp_f32_e32 v86, v93
	s_add_i32 s66, s4, s12
	s_lshl_b64 s[4:5], s[66:67], 1
	v_mul_u32_u24_e32 v4, 0x880, v4
	s_add_u32 s4, s8, s4
	s_mul_i32 s6, s13, 0x880
	v_add_u32_e32 v12, 0, v96
	v_lshl_add_u32 v123, v92, 2, 0
	v_lshlrev_b32_e32 v5, 9, v5
	v_sub_u32_e32 v126, 0, v64
	v_lshlrev_b32_e32 v64, 1, v4
	s_addc_u32 s5, s9, s5
	v_mov_b32_e32 v0, 0
	s_mov_b32 s7, 0
	v_mov_b32_e32 v99, v98
	v_mov_b32_e32 v100, v86
	v_mov_b32_e32 v101, v86
	v_mov_b32_e32 v91, v92
	v_mov_b32_e32 v102, v88
	v_mov_b32_e32 v103, v88
	v_add_u32_e32 v124, 32, v10
	v_or_b32_e32 v125, s6, v3
	v_lshl_add_u64 v[114:115], s[4:5], 0, v[64:65]
	v_add_u32_e32 v127, v9, v6
	v_add_u32_e32 v128, v12, v8
	v_add_u32_e32 v129, v123, v5
	s_lshl_b32 s66, s14, 1
	v_mov_b32_e32 v1, v0
	v_mov_b32_e32 v2, v0
	v_mov_b32_e32 v3, v0
	v_mov_b32_e32 v4, v0
	v_mov_b32_e32 v5, v0
	v_mov_b32_e32 v6, v0
	v_mov_b32_e32 v7, v0
	v_mov_b32_e32 v8, v0
	v_mov_b32_e32 v9, v0
	v_mov_b32_e32 v10, v0
	v_mov_b32_e32 v11, v0
	v_mov_b32_e32 v12, v0
	v_mov_b32_e32 v13, v0
	v_mov_b32_e32 v14, v0
	v_mov_b32_e32 v15, v0
	v_lshlrev_b32_e32 v206, 1, v94
	v_add_u32_e32 v206, s14, v206
	v_lshlrev_b32_e32 v207, 1, v90
	v_sub_u32_e32 v206, v206, v207
	v_add_u32_e32 v206, 0x400, v206
	v_mov_b32_e32 v207, 0
	v_and_b32_e32 v232, 32, v162
	v_lshrrev_b32_e32 v232, 2, v232
	v_mov_b32_e32 v233, 0
	v_lshl_add_u64 v[108:109], v[108:109], 0, v[232:233]
	v_lshl_add_u64 v[110:111], v[110:111], 0, v[232:233]
.LBB0_268:
	s_nop 2
	s_lshl_b32 s4, s7, 7
	s_add_i32 s4, s4, s6
	v_or_b32_e32 v64, s4, v92
	s_movk_i32 s4, 0x2200
	v_mad_u64_u32 v[116:117], s[4:5], v64, s4, 0
	v_lshl_add_u64 v[228:229], v[116:117], 1, v[104:105]
	global_load_dwordx4 v[66:69], v[228:229], off offset:2048
	global_load_dwordx4 v[70:73], v[228:229], off offset:2080
	global_load_dwordx4 v[74:77], v[228:229], off offset:2112
	global_load_dwordx4 v[78:81], v[228:229], off offset:2144
	v_lshl_add_u64 v[184:185], v[228:229], 0, v[206:207]
	global_load_dwordx2 v[186:187], v[184:185], off offset:2048
	global_load_dwordx2 v[188:189], v[184:185], off offset:2064
	global_load_dwordx2 v[190:191], v[184:185], off offset:2080
	global_load_dwordx2 v[192:193], v[184:185], off offset:2096
	global_load_dwordx2 v[194:195], v[184:185], off offset:2112
	global_load_dwordx2 v[196:197], v[184:185], off offset:2128
	global_load_dwordx2 v[198:199], v[184:185], off offset:2144
	global_load_dwordx2 v[200:201], v[184:185], off offset:2160
	v_mov_b64_e32 v[118:119], v[110:111]
	v_mov_b64_e32 v[120:121], v[108:109]
	s_mov_b32 s8, 0
	v_mad_u64_u32 v[130:131], s[10:11], v125, s49, v[104:105]
	global_load_dwordx4 v[132:135], v[130:131], off offset:2560
	global_load_dwordx4 v[136:139], v[130:131], off offset:2592
	global_load_dwordx4 v[140:143], v[130:131], off offset:2624
	global_load_dwordx4 v[144:147], v[130:131], off offset:2656
	global_load_dwordx4 v[168:171], v[120:121], off offset:-32
	global_load_dwordx4 v[172:175], v[120:121], off
	global_load_dwordx4 v[176:179], v[118:119], off offset:-32
	global_load_dwordx4 v[180:183], v[118:119], off
	v_cvt_pk_bf16_f32 v16, v0, s0
	s_barrier
; #define MFMA32(a, b, c) __builtin_amdgcn_mfma_f32_32x32x16_bf16((a), (b), (c), 0, 0, 0)
;     DEVINL bf16_t* Z() const { return (bf16_t*)(ws + OFF_Z); }
; DEVINL unsigned cvt_pk_bf16(float lo, float hi) { const f32x2 v = {lo, hi}; return __builtin_bit_cast(unsigned, __builtin_convertvector(v, bf16x2v)); }
; DEVINL void ret_block(const Ctx& c, int b, int hd, unsigned char* lds) {
;     ...
;         for (int i = 0; i < 16; ++i) {
;             const int dv = dvt * 32 + (i & 3) + 8 * (i >> 2) + 4 * h;
;             ST[dv * 72 + dt * 32 + r] = f2bf(sacc[i]);
;         }
;         __syncthreads();
;         const int ql = qs * 32 + r;
;         bf16x8 qf[4];
;         const bf16_t* qp = c.Z() + (size_t)(t0 + ql) * ZW + Z_BQ + hd * 64 + 8 * h;
; #pragma unroll
;         for (int s = 0; s < 4; ++s) qf[s] = *(const bf16x8*)(qp + 16 * s);
;         f32x16 o[2];
; #pragma unroll
;         for (int d = 0; d < 2; ++d) {
; #pragma unroll
;             for (int i = 0; i < 16; ++i) o[d][i] = 0.f;
; #pragma unroll
;             for (int s = 0; s < 4; ++s) {
;                 const bf16x8 sf = *(const bf16x8*)(ST + (dh * 64 + d * 32 + r) * 72 + 16 * s + 8 * h);
;                 o[d] = MFMA32(sf, qf[s], o[d]);
;             }
; #pragma unroll
;             for (int i = 0; i < 16; ++i) o[d][i] *= gam;
;         }
;         for (int kt = 0; kt <= qs; ++kt) {
;             const bf16_t* kp = c.Z() + (size_t)(t0 + kt * 32 + r) * ZW + Z_BK + hd * 64 + 8 * h;
;             f32x16 st;
; #pragma unroll
;             for (int i = 0; i < 16; ++i) st[i] = 0.f;
; #pragma unroll
;             for (int s = 0; s < 4; ++s) { const bf16x8 kf = *(const bf16x8*)(kp + 16 * s); st = MFMA32(kf, qf[s], st); }
;             bf16x8 pf[2];
; #pragma unroll
;             for (int s = 0; s < 2; ++s) {
;                 u32x4 pk;
; #pragma unroll
;                 for (int jj = 0; jj < 4; ++jj) {
;                     float a2[2];
; #pragma unroll
;                     for (int e = 0; e < 2; ++e) {
;                         const int i = 8 * s + 2 * jj + e;
;                         const int kl = kt * 32 + (i & 3) + 8 * (i >> 2) + 4 * h;
;                         a2[e] = (kl <= ql) ? st[i] * fexp2(-lg2 * (float)kl) : 0.f;
;                     }
;                     pk[jj] = cvt_pk_bf16(a2[0], a2[1]);
;                 }
;                 pf[s] = __builtin_bit_cast(bf16x8, pk);
;             }
	ds_write_b16 v127, v16
	v_cvt_pk_bf16_f32 v16, v1, s0
	ds_write_b16 v127, v16 offset:144
	v_cvt_pk_bf16_f32 v16, v2, s0
	ds_write_b16 v127, v16 offset:288
	v_cvt_pk_bf16_f32 v16, v3, s0
	ds_write_b16 v127, v16 offset:432
	v_cvt_pk_bf16_f32 v16, v4, s0
	ds_write_b16 v127, v16 offset:1152
	v_cvt_pk_bf16_f32 v16, v5, s0
	ds_write_b16 v127, v16 offset:1296
	v_cvt_pk_bf16_f32 v16, v6, s0
	ds_write_b16 v127, v16 offset:1440
	v_cvt_pk_bf16_f32 v16, v7, s0
	ds_write_b16 v127, v16 offset:1584
	v_cvt_pk_bf16_f32 v16, v8, s0
	ds_write_b16 v127, v16 offset:2304
	v_cvt_pk_bf16_f32 v16, v9, s0
	ds_write_b16 v127, v16 offset:2448
	v_cvt_pk_bf16_f32 v16, v10, s0
	ds_write_b16 v127, v16 offset:2592
	v_cvt_pk_bf16_f32 v16, v11, s0
	ds_write_b16 v127, v16 offset:2736
	v_cvt_pk_bf16_f32 v16, v12, s0
	ds_write_b16 v127, v16 offset:3456
	v_cvt_pk_bf16_f32 v16, v13, s0
	ds_write_b16 v127, v16 offset:3600
	v_cvt_pk_bf16_f32 v16, v14, s0
	ds_write_b16 v127, v16 offset:3744
	v_cvt_pk_bf16_f32 v16, v15, s0
	ds_write_b16 v127, v16 offset:3888
	s_waitcnt lgkmcnt(0)
	s_barrier
	ds_read_b128 v[16:19], v128
	ds_read_b128 v[20:23], v128 offset:32
	v_mov_b32_e32 v87, v86
	s_waitcnt vmcnt(19) lgkmcnt(1)
	v_mfma_f32_32x32x16_bf16 v[32:47], v[16:19], v[66:69], 0
	ds_read_b128 v[16:19], v128 offset:64
	ds_read_b128 v[48:51], v128 offset:4640
	s_waitcnt vmcnt(18) lgkmcnt(2)
	v_mfma_f32_32x32x16_bf16 v[32:47], v[20:23], v[70:73], v[32:47]
	s_waitcnt vmcnt(17) lgkmcnt(1)
	v_mfma_f32_32x32x16_bf16 v[32:47], v[16:19], v[74:77], v[32:47]
	ds_read_b128 v[16:19], v128 offset:96
	s_waitcnt vmcnt(16) lgkmcnt(0)
	v_mfma_f32_32x32x16_bf16 v[32:47], v[16:19], v[78:81], v[32:47]
	ds_read_b128 v[16:19], v128 offset:4608
	s_waitcnt lgkmcnt(0)
	v_mfma_f32_32x32x16_bf16 v[16:31], v[16:19], v[66:69], 0
	s_nop 8
	v_mul_f32_e64 v46, v86, v46
	v_mul_f32_e64 v47, v87, v47
	v_mul_f32_e64 v44, v86, v44
	v_mul_f32_e64 v45, v87, v45
	v_mul_f32_e64 v42, v86, v42
	v_mul_f32_e64 v43, v87, v43
	v_pk_mul_f32 v[40:41], v[86:87], v[40:41]
	v_pk_mul_f32 v[38:39], v[86:87], v[38:39]
	v_pk_mul_f32 v[36:37], v[86:87], v[36:37]
	v_pk_mul_f32 v[34:35], v[86:87], v[34:35]
	v_mfma_f32_32x32x16_bf16 v[16:31], v[48:51], v[70:73], v[16:31]
	ds_read_b128 v[48:51], v128 offset:4672
	v_mul_f32_e64 v32, v100, v32
	v_mul_f32_e64 v33, v101, v33
	s_waitcnt lgkmcnt(0)
	v_mfma_f32_32x32x16_bf16 v[16:31], v[48:51], v[74:77], v[16:31]
	ds_read_b128 v[48:51], v128 offset:4704
	s_waitcnt lgkmcnt(0)
	v_mfma_f32_32x32x16_bf16 v[16:31], v[48:51], v[78:81], v[16:31]
	s_nop 11
	v_pk_mul_f32 v[30:31], v[86:87], v[30:31]
	v_pk_mul_f32 v[28:29], v[86:87], v[28:29]
	v_pk_mul_f32 v[26:27], v[86:87], v[26:27]
	v_pk_mul_f32 v[24:25], v[86:87], v[24:25]
	v_pk_mul_f32 v[22:23], v[86:87], v[22:23]
	v_pk_mul_f32 v[20:21], v[86:87], v[20:21]
	v_pk_mul_f32 v[18:19], v[86:87], v[18:19]
	v_pk_mul_f32 v[16:17], v[86:87], v[16:17]
.LBB0_269:
	v_add_u32_e32 v87, s8, v90
	v_cmp_le_u32_e32 vcc, v87, v92
	s_add_i32 s8, s8, 32
	v_cmp_eq_u32_e64 s[12:13], s8, v124
	s_waitcnt vmcnt(7)
	v_mfma_f32_32x32x16_bf16 v[48:63], v[132:135], v[66:69], 0
	s_waitcnt vmcnt(6)
	v_mfma_f32_32x32x16_bf16 v[48:63], v[136:139], v[70:73], v[48:63]
	s_waitcnt vmcnt(5)
	v_mfma_f32_32x32x16_bf16 v[48:63], v[140:143], v[74:77], v[48:63]
	s_waitcnt vmcnt(4)
	v_mfma_f32_32x32x16_bf16 v[48:63], v[144:147], v[78:81], v[48:63]
	s_cmp_lg_u64 s[12:13], 0
	s_cbranch_scc1 .Lret_last_tile
	v_add_u32_e32 v230, s8, v125
	v_mad_u64_u32 v[130:131], s[10:11], v230, s49, v[104:105]
	global_load_dwordx4 v[132:135], v[130:131], off offset:2560
	global_load_dwordx4 v[136:139], v[130:131], off offset:2592
	global_load_dwordx4 v[140:143], v[130:131], off offset:2624
	global_load_dwordx4 v[144:147], v[130:131], off offset:2656
	v_cvt_f32_u32_e32 v82, v87
	v_or_b32_e32 v83, 3, v87
	v_or_b32_e32 v84, 2, v87
	v_mul_f32_e64 v82, -v93, v82
	v_exp_f32_e32 v82, v82
	s_nop 6
	v_mul_f32_e32 v48, v82, v48
	v_add_u32_e32 v82, 1, v87
	v_cvt_f32_u32_e32 v82, v82
	v_cndmask_b32_e32 v48, 0, v48, vcc
	v_cmp_lt_u32_e32 vcc, v87, v92
	v_mul_f32_e64 v82, -v93, v82
	v_exp_f32_e32 v82, v82
	s_nop 0
	v_mul_f32_e32 v49, v82, v49
	v_cndmask_b32_e32 v49, 0, v49, vcc
	v_cvt_pk_bf16_f32 v82, v48, v49
	v_cvt_f32_u32_e32 v48, v84
	v_cvt_f32_u32_e32 v49, v83
	v_cmp_le_u32_e32 vcc, v84, v92
	v_mul_f32_e64 v48, -v93, v48
	v_mul_f32_e64 v49, -v93, v49
	v_exp_f32_e32 v48, v48
	v_exp_f32_e32 v49, v49
	s_nop 0
	v_pk_mul_f32 v[48:49], v[48:49], v[50:51]
	s_nop 0
	v_cvt_pk_bf16_f32 v48, v48, v49
	v_cndmask_b32_e32 v49, 0, v48, vcc
	v_lshrrev_b32_e32 v48, 16, v48
	v_cmp_le_u32_e32 vcc, v83, v91
	v_or_b32_e32 v50, 9, v87
	v_or_b32_e32 v51, 8, v87
	v_cndmask_b32_e32 v48, 0, v48, vcc
	v_perm_b32 v83, v48, v49, s46
	v_cvt_f32_u32_e32 v48, v51
	v_cvt_f32_u32_e32 v49, v50
	v_cmp_le_u32_e32 vcc, v51, v92
	v_or_b32_e32 v51, 10, v87
	v_mul_f32_e64 v48, -v93, v48
	v_mul_f32_e64 v49, -v93, v49
	v_exp_f32_e32 v48, v48
	v_exp_f32_e32 v49, v49
	s_nop 0
	v_pk_mul_f32 v[48:49], v[48:49], v[52:53]
	s_nop 0
	v_cvt_pk_bf16_f32 v48, v48, v49
	v_cndmask_b32_e32 v49, 0, v48, vcc
	v_lshrrev_b32_e32 v48, 16, v48
	v_cmp_le_u32_e32 vcc, v50, v91
	v_or_b32_e32 v50, 11, v87
	v_or_b32_e32 v52, 18, v87
	v_cndmask_b32_e32 v48, 0, v48, vcc
	v_perm_b32 v84, v48, v49, s46
	v_cvt_f32_u32_e32 v48, v51
	v_cvt_f32_u32_e32 v49, v50
	v_cmp_le_u32_e32 vcc, v51, v92
	v_or_b32_e32 v51, 16, v87
	v_mul_f32_e64 v48, -v93, v48
	v_mul_f32_e64 v49, -v93, v49
	v_exp_f32_e32 v48, v48
	v_exp_f32_e32 v49, v49
	v_or_b32_e32 v53, 24, v87
	v_pk_mul_f32 v[48:49], v[48:49], v[54:55]
	s_nop 0
	v_cvt_pk_bf16_f32 v48, v48, v49
	v_cndmask_b32_e32 v49, 0, v48, vcc
	v_lshrrev_b32_e32 v48, 16, v48
; #define MFMA32(a, b, c) __builtin_amdgcn_mfma_f32_32x32x16_bf16((a), (b), (c), 0, 0, 0)
;     DEVINL bf16_t* Z() const { return (bf16_t*)(ws + OFF_Z); }
; DEVINL unsigned cvt_pk_bf16(float lo, float hi) { const f32x2 v = {lo, hi}; return __builtin_bit_cast(unsigned, __builtin_convertvector(v, bf16x2v)); }
; DEVINL float fexp2(float x) { return __builtin_amdgcn_exp2f(x); }
; DEVINL void ret_block(const Ctx& c, int b, int hd, unsigned char* lds) {
;     ...
;         for (int kt = 0; kt <= qs; ++kt) {
;             const bf16_t* kp = c.Z() + (size_t)(t0 + kt * 32 + r) * ZW + Z_BK + hd * 64 + 8 * h;
;             f32x16 st;
; #pragma unroll
;             for (int i = 0; i < 16; ++i) st[i] = 0.f;
; #pragma unroll
;             for (int s = 0; s < 4; ++s) { const bf16x8 kf = *(const bf16x8*)(kp + 16 * s); st = MFMA32(kf, qf[s], st); }
;             bf16x8 pf[2];
; #pragma unroll
;             for (int s = 0; s < 2; ++s) {
;                 u32x4 pk;
; #pragma unroll
;                 for (int jj = 0; jj < 4; ++jj) {
;                     float a2[2];
; #pragma unroll
;                     for (int e = 0; e < 2; ++e) {
;                         const int i = 8 * s + 2 * jj + e;
;                         const int kl = kt * 32 + (i & 3) + 8 * (i >> 2) + 4 * h;
;                         a2[e] = (kl <= ql) ? st[i] * fexp2(-lg2 * (float)kl) : 0.f;
;                     }
;                     pk[jj] = cvt_pk_bf16(a2[0], a2[1]);
;                 }
;                 pf[s] = __builtin_bit_cast(bf16x8, pk);
;             }
; #pragma unroll
;             for (int d = 0; d < 2; ++d) {
;                 const bf16_t* vp = vtb + (size_t)(dh * 64 + d * 32 + r) * L + p0 + kt * 32 + 4 * h;
; #pragma unroll
;                 for (int s = 0; s < 2; ++s) {
;                     const u32x2 lo = *(const u32x2*)(vp + 16 * s), hi = *(const u32x2*)(vp + 16 * s + 8);
;                     u32x4 vv = {lo[0], lo[1], hi[0], hi[1]};
;                     o[d] = MFMA32(__builtin_bit_cast(bf16x8, vv), pf[s], o[d]);
;                 }
;             }
;         }
	v_cmp_le_u32_e32 vcc, v50, v91
	v_or_b32_e32 v50, 17, v87
	v_or_b32_e32 v54, 26, v87
	v_cndmask_b32_e32 v48, 0, v48, vcc
	v_perm_b32 v85, v48, v49, s46
	v_cvt_f32_u32_e32 v48, v51
	v_cvt_f32_u32_e32 v49, v50
	v_cmp_le_u32_e32 vcc, v51, v92
	v_mul_f32_e64 v48, -v93, v48
	v_mul_f32_e64 v49, -v93, v49
	v_exp_f32_e32 v48, v48
	v_exp_f32_e32 v49, v49
	s_nop 0
	v_pk_mul_f32 v[48:49], v[48:49], v[56:57]
	s_nop 0
	v_cvt_pk_bf16_f32 v48, v48, v49
	v_cndmask_b32_e32 v49, 0, v48, vcc
	v_lshrrev_b32_e32 v48, 16, v48
	v_cmp_le_u32_e32 vcc, v50, v91
	v_cvt_f32_u32_e32 v50, v52
	v_mul_f32_e64 v50, -v93, v50
	v_cndmask_b32_e32 v48, 0, v48, vcc
	v_perm_b32 v48, v48, v49, s46
	v_or_b32_e32 v49, 19, v87
	v_cvt_f32_u32_e32 v51, v49
	v_exp_f32_e32 v50, v50
	v_cmp_le_u32_e32 vcc, v52, v92
	v_or_b32_e32 v52, 25, v87
	v_mul_f32_e64 v51, -v93, v51
	v_exp_f32_e32 v51, v51
	s_nop 0
	v_pk_mul_f32 v[50:51], v[50:51], v[58:59]
	s_nop 0
	v_cvt_pk_bf16_f32 v50, v50, v51
	v_cndmask_b32_e32 v51, 0, v50, vcc
	v_lshrrev_b32_e32 v50, 16, v50
	v_cmp_le_u32_e32 vcc, v49, v91
	s_nop 1
	v_cndmask_b32_e32 v49, 0, v50, vcc
	v_perm_b32 v49, v49, v51, s46
	v_cvt_f32_u32_e32 v50, v53
	v_cvt_f32_u32_e32 v51, v52
	v_cmp_le_u32_e32 vcc, v53, v92
	v_mul_f32_e64 v50, -v93, v50
	v_mul_f32_e64 v51, -v93, v51
	v_exp_f32_e32 v50, v50
	v_exp_f32_e32 v51, v51
	s_nop 0
	v_pk_mul_f32 v[50:51], v[50:51], v[60:61]
	s_nop 0
	v_cvt_pk_bf16_f32 v50, v50, v51
	v_cndmask_b32_e32 v51, 0, v50, vcc
	v_lshrrev_b32_e32 v50, 16, v50
	v_cmp_le_u32_e32 vcc, v52, v91
	v_cvt_f32_u32_e32 v52, v54
	v_mul_f32_e64 v52, -v93, v52
	v_cndmask_b32_e32 v50, 0, v50, vcc
	v_perm_b32 v50, v50, v51, s46
	v_or_b32_e32 v51, 27, v87
	v_cvt_f32_u32_e32 v53, v51
	v_exp_f32_e32 v52, v52
	v_cmp_le_u32_e32 vcc, v54, v92
	v_mul_f32_e64 v53, -v93, v53
	v_exp_f32_e32 v53, v53
	s_nop 0
	v_pk_mul_f32 v[52:53], v[52:53], v[62:63]
	s_nop 0
	v_cvt_pk_bf16_f32 v52, v52, v53
	v_cndmask_b32_e32 v53, 0, v52, vcc
	v_lshrrev_b32_e32 v52, 16, v52
	v_cmp_le_u32_e32 vcc, v51, v91
	s_nop 1
	v_cndmask_b32_e32 v51, 0, v52, vcc
	v_perm_b32 v51, v51, v53, s46
	s_waitcnt vmcnt(7)
	v_permlane32_swap_b32 v168, v170
	v_permlane32_swap_b32 v169, v171
	s_waitcnt vmcnt(6)
	v_permlane32_swap_b32 v172, v174
	v_permlane32_swap_b32 v173, v175
	v_mfma_f32_32x32x16_bf16 v[32:47], v[168:171], v[82:85], v[32:47]
	s_waitcnt vmcnt(5)
	v_permlane32_swap_b32 v176, v178
	v_permlane32_swap_b32 v177, v179
	v_mfma_f32_32x32x16_bf16 v[32:47], v[172:175], v[48:51], v[32:47]
	s_waitcnt vmcnt(4)
	v_permlane32_swap_b32 v180, v182
	v_permlane32_swap_b32 v181, v183
	v_mfma_f32_32x32x16_bf16 v[16:31], v[176:179], v[82:85], v[16:31]
	v_lshl_add_u64 v[120:121], v[120:121], 0, 64
	v_lshl_add_u64 v[118:119], v[118:119], 0, 64
	s_nop 0
	v_mfma_f32_32x32x16_bf16 v[16:31], v[180:183], v[48:51], v[16:31]
	global_load_dwordx4 v[168:171], v[120:121], off offset:-32
	global_load_dwordx4 v[172:175], v[120:121], off
	global_load_dwordx4 v[176:179], v[118:119], off offset:-32
	global_load_dwordx4 v[180:183], v[118:119], off
	s_branch .LBB0_269
.Lret_last_tile:
	v_cvt_f32_u32_e32 v82, v87
	v_or_b32_e32 v83, 3, v87
	v_or_b32_e32 v84, 2, v87
	v_mul_f32_e64 v82, -v93, v82
	v_exp_f32_e32 v82, v82
	s_nop 6
	v_mul_f32_e32 v48, v82, v48
	v_add_u32_e32 v82, 1, v87
	v_cvt_f32_u32_e32 v82, v82
	v_cndmask_b32_e32 v48, 0, v48, vcc
	v_cmp_lt_u32_e32 vcc, v87, v92
	v_mul_f32_e64 v82, -v93, v82
	v_exp_f32_e32 v82, v82
	s_nop 0
	v_mul_f32_e32 v49, v82, v49
	v_cndmask_b32_e32 v49, 0, v49, vcc
	v_cvt_pk_bf16_f32 v82, v48, v49
	v_cvt_f32_u32_e32 v48, v84
	v_cvt_f32_u32_e32 v49, v83
	v_cmp_le_u32_e32 vcc, v84, v92
	v_mul_f32_e64 v48, -v93, v48
	v_mul_f32_e64 v49, -v93, v49
	v_exp_f32_e32 v48, v48
	v_exp_f32_e32 v49, v49
	s_nop 0
	v_pk_mul_f32 v[48:49], v[48:49], v[50:51]
	s_nop 0
	v_cvt_pk_bf16_f32 v48, v48, v49
	v_cndmask_b32_e32 v49, 0, v48, vcc
	v_lshrrev_b32_e32 v48, 16, v48
	v_cmp_le_u32_e32 vcc, v83, v91
	v_or_b32_e32 v50, 9, v87
	v_or_b32_e32 v51, 8, v87
	v_cndmask_b32_e32 v48, 0, v48, vcc
	v_perm_b32 v83, v48, v49, s46
	v_cvt_f32_u32_e32 v48, v51
	v_cvt_f32_u32_e32 v49, v50
	v_cmp_le_u32_e32 vcc, v51, v92
	v_or_b32_e32 v51, 10, v87
	v_mul_f32_e64 v48, -v93, v48
	v_mul_f32_e64 v49, -v93, v49
	v_exp_f32_e32 v48, v48
	v_exp_f32_e32 v49, v49
	s_nop 0
	v_pk_mul_f32 v[48:49], v[48:49], v[52:53]
	s_nop 0
	v_cvt_pk_bf16_f32 v48, v48, v49
	v_cndmask_b32_e32 v49, 0, v48, vcc
	v_lshrrev_b32_e32 v48, 16, v48
	v_cmp_le_u32_e32 vcc, v50, v91
	v_or_b32_e32 v50, 11, v87
	v_or_b32_e32 v52, 18, v87
	v_cndmask_b32_e32 v48, 0, v48, vcc
	v_perm_b32 v84, v48, v49, s46
	v_cvt_f32_u32_e32 v48, v51
	v_cvt_f32_u32_e32 v49, v50
	v_cmp_le_u32_e32 vcc, v51, v92
	v_or_b32_e32 v51, 16, v87
	v_mul_f32_e64 v48, -v93, v48
	v_mul_f32_e64 v49, -v93, v49
	v_exp_f32_e32 v48, v48
	v_exp_f32_e32 v49, v49
	v_or_b32_e32 v53, 24, v87
	v_pk_mul_f32 v[48:49], v[48:49], v[54:55]
	s_nop 0
	v_cvt_pk_bf16_f32 v48, v48, v49
	v_cndmask_b32_e32 v49, 0, v48, vcc
	v_lshrrev_b32_e32 v48, 16, v48
	v_cmp_le_u32_e32 vcc, v50, v91
	v_or_b32_e32 v50, 17, v87
	v_or_b32_e32 v54, 26, v87
	v_cndmask_b32_e32 v48, 0, v48, vcc
	v_perm_b32 v85, v48, v49, s46
	v_cvt_f32_u32_e32 v48, v51
	v_cvt_f32_u32_e32 v49, v50
	v_cmp_le_u32_e32 vcc, v51, v92
	v_mul_f32_e64 v48, -v93, v48
	v_mul_f32_e64 v49, -v93, v49
	v_exp_f32_e32 v48, v48
	v_exp_f32_e32 v49, v49
	s_nop 0
	v_pk_mul_f32 v[48:49], v[48:49], v[56:57]
	s_nop 0
	v_cvt_pk_bf16_f32 v48, v48, v49
	v_cndmask_b32_e32 v49, 0, v48, vcc
	v_lshrrev_b32_e32 v48, 16, v48
	v_cmp_le_u32_e32 vcc, v50, v91
	v_cvt_f32_u32_e32 v50, v52
	v_mul_f32_e64 v50, -v93, v50
	v_cndmask_b32_e32 v48, 0, v48, vcc
	v_perm_b32 v48, v48, v49, s46
; DEVINL void ret_block(const Ctx& c, int b, int hd, unsigned char* lds) {
;     ...
;             for (int d = 0; d < 2; ++d) {
;                 const bf16_t* vp = vtb + (size_t)(dh * 64 + d * 32 + r) * L + p0 + kt * 32 + 4 * h;
; #pragma unroll
;                 for (int s = 0; s < 2; ++s) {
;                     const u32x2 lo = *(const u32x2*)(vp + 16 * s), hi = *(const u32x2*)(vp + 16 * s + 8);
;                     u32x4 vv = {lo[0], lo[1], hi[0], hi[1]};
;                     o[d] = MFMA32(__builtin_bit_cast(bf16x8, vv), pf[s], o[d]);
;                 }
;             }
;         }
;         const float gq = fexp2(lg2 * (float)ql);
;         float ss = 0.f;
; #pragma unroll
;         for (int d = 0; d < 2; ++d)
; #pragma unroll
;             for (int i = 0; i < 16; ++i) { o[d][i] *= gq; ss += o[d][i] * o[d][i]; }
;         ss += __shfl_xor(ss, 32);
;         if (h == 0) ssq[dh * 128 + ql] = ss;
;         __syncthreads();
;         const float rs = rsqrtf((ssq[ql] + ssq[128 + ql]) * (1.f / 128.f) + 1e-6f);
;         {
;             const bf16_t* gp = c.Z() + (size_t)(t0 + ql) * ZW + Z_BG + hd * 128 + dh * 64;
;             bf16_t* yp = Y + (size_t)(t0 + ql) * 512 + hd * 128 + dh * 64;
; #pragma unroll
;             for (int d = 0; d < 2; ++d)
; #pragma unroll
;                 for (int g = 0; g < 4; ++g) {
;                     const int dl = d * 32 + 8 * g + 4 * h;
;                     const u32x2 gg = *(const u32x2*)(gp + dl);
;                     float gv[4] = {bflo(gg[0]), bfhi(gg[0]), bflo(gg[1]), bfhi(gg[1])};
;                     float ov[4];
; #pragma unroll
;                     for (int j = 0; j < 4; ++j) { const float sg = gv[j] * sigmoidf_(gv[j]); ov[j] = sg * o[d][4 * g + j] * rs; }
;                     u32x2 pk; pk[0] = cvt_pk_bf16(ov[0], ov[1]); pk[1] = cvt_pk_bf16(ov[2], ov[3]);
;                     *(u32x2*)(yp + dl) = pk;
;                 }
;         }
; #pragma unroll
;         for (int i = 0; i < 16; ++i) sacc[i] *= gam128;
;         {
;             const bf16_t* va = vtb + (size_t)(dvt * 32 + r) * L + p0 + 8 * h;
;             const bf16_t* kb = ktb + (size_t)(dt * 32 + r) * L + p0 + 8 * h;
; #pragma unroll 2
;             for (int ks = 0; ks < 8; ++ks) {
;                 const bf16x8 vf = *(const bf16x8*)(va + 16 * ks);
;                 const u32x4 kr = *(const u32x4*)(kb + 16 * ks);
	v_or_b32_e32 v49, 19, v87
	v_cvt_f32_u32_e32 v51, v49
	v_exp_f32_e32 v50, v50
	v_cmp_le_u32_e32 vcc, v52, v92
	v_or_b32_e32 v52, 25, v87
	v_mul_f32_e64 v51, -v93, v51
	v_exp_f32_e32 v51, v51
	s_nop 0
	v_pk_mul_f32 v[50:51], v[50:51], v[58:59]
	s_nop 0
	v_cvt_pk_bf16_f32 v50, v50, v51
	v_cndmask_b32_e32 v51, 0, v50, vcc
	v_lshrrev_b32_e32 v50, 16, v50
	v_cmp_le_u32_e32 vcc, v49, v91
	s_nop 1
	v_cndmask_b32_e32 v49, 0, v50, vcc
	v_perm_b32 v49, v49, v51, s46
	v_cvt_f32_u32_e32 v50, v53
	v_cvt_f32_u32_e32 v51, v52
	v_cmp_le_u32_e32 vcc, v53, v92
	v_mul_f32_e64 v50, -v93, v50
	v_mul_f32_e64 v51, -v93, v51
	v_exp_f32_e32 v50, v50
	v_exp_f32_e32 v51, v51
	s_nop 0
	v_pk_mul_f32 v[50:51], v[50:51], v[60:61]
	s_nop 0
	v_cvt_pk_bf16_f32 v50, v50, v51
	v_cndmask_b32_e32 v51, 0, v50, vcc
	v_lshrrev_b32_e32 v50, 16, v50
	v_cmp_le_u32_e32 vcc, v52, v91
	v_cvt_f32_u32_e32 v52, v54
	v_mul_f32_e64 v52, -v93, v52
	v_cndmask_b32_e32 v50, 0, v50, vcc
	v_perm_b32 v50, v50, v51, s46
	v_or_b32_e32 v51, 27, v87
	v_cvt_f32_u32_e32 v53, v51
	v_exp_f32_e32 v52, v52
	v_cmp_le_u32_e32 vcc, v54, v92
	v_mul_f32_e64 v53, -v93, v53
	v_exp_f32_e32 v53, v53
	s_nop 0
	v_pk_mul_f32 v[52:53], v[52:53], v[62:63]
	s_nop 0
	v_cvt_pk_bf16_f32 v52, v52, v53
	v_cndmask_b32_e32 v53, 0, v52, vcc
	v_lshrrev_b32_e32 v52, 16, v52
	v_cmp_le_u32_e32 vcc, v51, v91
	s_nop 1
	v_cndmask_b32_e32 v51, 0, v52, vcc
	v_perm_b32 v51, v51, v53, s46
	s_waitcnt vmcnt(3)
	v_permlane32_swap_b32 v168, v170
	v_permlane32_swap_b32 v169, v171
	s_waitcnt vmcnt(2)
	v_permlane32_swap_b32 v172, v174
	v_permlane32_swap_b32 v173, v175
	v_mfma_f32_32x32x16_bf16 v[32:47], v[168:171], v[82:85], v[32:47]
	s_waitcnt vmcnt(1)
	v_permlane32_swap_b32 v176, v178
	v_permlane32_swap_b32 v177, v179
	v_mfma_f32_32x32x16_bf16 v[32:47], v[172:175], v[48:51], v[32:47]
	s_waitcnt vmcnt(0)
	v_permlane32_swap_b32 v180, v182
	v_permlane32_swap_b32 v181, v183
	v_mfma_f32_32x32x16_bf16 v[16:31], v[176:179], v[82:85], v[16:31]
	s_nop 0
	v_mfma_f32_32x32x16_bf16 v[16:31], v[180:183], v[48:51], v[16:31]
	s_mov_b64 s[4:5], 0x15b40000
	v_lshl_add_u64 v[202:203], v[112:113], 0, v[96:97]
	v_lshl_add_u64 v[202:203], v[202:203], 0, s[4:5]
	s_mov_b64 s[4:5], 0x17080000
	v_lshl_add_u64 v[204:205], v[114:115], 0, v[96:97]
	v_lshl_add_u64 v[204:205], v[204:205], 0, s[4:5]
	global_load_dwordx4 v[132:135], v[202:203], off
	global_load_dwordx4 v[136:139], v[204:205], off
	global_load_dwordx4 v[140:143], v[202:203], off offset:32
	global_load_dwordx4 v[144:147], v[204:205], off offset:32
	global_load_dwordx4 v[148:151], v[202:203], off offset:64
	global_load_dwordx4 v[152:155], v[204:205], off offset:64
	global_load_dwordx4 v[156:159], v[202:203], off offset:96
	global_load_dwordx4 v[168:171], v[204:205], off offset:96
	global_load_dwordx4 v[172:175], v[202:203], off offset:128
	global_load_dwordx4 v[176:179], v[204:205], off offset:128
	global_load_dwordx4 v[180:183], v[202:203], off offset:160
	global_load_dwordx4 v[208:211], v[204:205], off offset:160
	global_load_dwordx4 v[212:215], v[202:203], off offset:192
	global_load_dwordx4 v[216:219], v[204:205], off offset:192
	global_load_dwordx4 v[220:223], v[202:203], off offset:224
	global_load_dwordx4 v[224:227], v[204:205], off offset:224
	v_pk_mul_f32 v[58:59], v[98:99], v[32:33]
	v_pk_mul_f32 v[56:57], v[98:99], v[34:35]
	v_pk_mul_f32 v[60:61], v[58:59], v[58:59]
	v_pk_mul_f32 v[62:63], v[56:57], v[56:57]
	v_add_f32_e32 v60, v60, v61
	v_pk_mul_f32 v[54:55], v[98:99], v[36:37]
	v_add_f32_e32 v60, v62, v60
	v_pk_mul_f32 v[66:67], v[54:55], v[54:55]
	v_add_f32_e32 v60, v63, v60
	v_pk_mul_f32 v[52:53], v[98:99], v[38:39]
	v_add_f32_e32 v60, v66, v60
	v_pk_mul_f32 v[68:69], v[52:53], v[52:53]
	v_add_f32_e32 v60, v67, v60
	v_pk_mul_f32 v[50:51], v[98:99], v[40:41]
	v_add_f32_e32 v60, v68, v60
	v_pk_mul_f32 v[70:71], v[50:51], v[50:51]
	v_add_f32_e32 v60, v69, v60
	v_pk_mul_f32 v[48:49], v[98:99], v[42:43]
	v_add_f32_e32 v60, v70, v60
	v_pk_mul_f32 v[72:73], v[48:49], v[48:49]
	v_add_f32_e32 v60, v71, v60
	v_pk_mul_f32 v[44:45], v[98:99], v[44:45]
	v_add_f32_e32 v60, v72, v60
	v_pk_mul_f32 v[74:75], v[44:45], v[44:45]
	v_add_f32_e32 v60, v73, v60
	v_pk_mul_f32 v[42:43], v[98:99], v[46:47]
	v_add_f32_e32 v60, v74, v60
	v_pk_mul_f32 v[46:47], v[42:43], v[42:43]
	v_add_f32_e32 v60, v75, v60
	v_pk_mul_f32 v[40:41], v[98:99], v[16:17]
	v_add_f32_e32 v46, v46, v60
	v_pk_mul_f32 v[76:77], v[40:41], v[40:41]
	v_add_f32_e32 v46, v47, v46
	v_pk_mul_f32 v[38:39], v[98:99], v[18:19]
	v_add_f32_e32 v46, v76, v46
	v_pk_mul_f32 v[18:19], v[38:39], v[38:39]
	v_add_f32_e32 v46, v77, v46
	v_pk_mul_f32 v[36:37], v[98:99], v[20:21]
	v_add_f32_e32 v18, v18, v46
	v_pk_mul_f32 v[78:79], v[36:37], v[36:37]
	v_add_f32_e32 v18, v19, v18
	v_pk_mul_f32 v[34:35], v[98:99], v[22:23]
	v_add_f32_e32 v18, v78, v18
	v_pk_mul_f32 v[22:23], v[34:35], v[34:35]
	v_add_f32_e32 v18, v79, v18
	v_pk_mul_f32 v[32:33], v[98:99], v[24:25]
	v_add_f32_e32 v18, v22, v18
	v_pk_mul_f32 v[24:25], v[32:33], v[32:33]
	v_add_f32_e32 v18, v23, v18
	v_pk_mul_f32 v[26:27], v[98:99], v[26:27]
	v_add_f32_e32 v18, v24, v18
	v_pk_mul_f32 v[80:81], v[26:27], v[26:27]
	v_add_f32_e32 v18, v25, v18
	v_pk_mul_f32 v[20:21], v[98:99], v[28:29]
	v_add_f32_e32 v18, v80, v18
	v_pk_mul_f32 v[28:29], v[20:21], v[20:21]
	v_add_f32_e32 v18, v81, v18
	v_pk_mul_f32 v[16:17], v[98:99], v[30:31]
	v_add_f32_e32 v18, v28, v18
	v_pk_mul_f32 v[30:31], v[16:17], v[16:17]
	v_add_f32_e32 v18, v29, v18
	v_add_f32_e32 v18, v30, v18
	v_add_f32_e32 v18, v31, v18
	ds_bpermute_b32 v19, v122, v18
	s_and_saveexec_b64 s[4:5], s[0:1]
	s_cbranch_execz .LBB0_272
	s_waitcnt lgkmcnt(0)
	v_add_f32_e32 v18, v18, v19
	ds_write_b32 v129, v18 offset:18432
